# loop-head alignment: .p2align 6 before the P1/P4/P5 K-loop heads (I-cache line alignment), otherwise v163
# speedup vs baseline: 1.0042x; 1.0042x over previous
; #define GP_STAGE(bufoff, gbase, voff) do { _Pragma("unroll") for (int _i = 0; _i < 2; ++_i) \
;         __builtin_amdgcn_global_load_lds((const unsigned*)((const char*)(gbase) + (voff)[_i]), (LAS unsigned*)(lds + (bufoff) + ldsw + _i * 8192), 16, 0, 0); } while (0)
; #define GP_LDA(dst, b, h) do { _Pragma("unroll") for (int m = 0; m < 4; ++m) _Pragma("unroll") for (int k = 0; k < 2; ++k) dst[m][k] = *(const LAS bf16x8*)(lds + GP_SA(b, h) + aoff + m * 2048 + k * 1024); } while (0)
; #define GP_LDB(dst, b, h) do { _Pragma("unroll") for (int n = 0; n < 2; ++n) _Pragma("unroll") for (int k = 0; k < 2; ++k) dst[n][k] = *(const LAS bf16x8*)(lds + GP_SB(b, h) + boff + n * 2048 + k * 1024); } while (0)
; #define GP_SCHED __builtin_amdgcn_sched_barrier(0)
; template <class Epi, class Sched>
; __device__ __forceinline__ void gemm_phase(LAS unsigned char* lds, const int lda, const int ldb, const int K, const Sched& S, const Epi& E, const int widx) {
;     ...
;         const bool has_next = S.next(ui + 1, nxt);
;         const char* nA = has_next ? nxt.A : cA; const char* nB = has_next ? nxt.B : cB;
;         for (int t = 0; t < nt; t += 2) {
;             const bool last = (t == nt - 2);
;             const char* a1 = cA + (size_t)(t + 1) * kstep;
;             const char* a2 = last ? nA : cA + (size_t)(t + 2) * kstep; const char* b2 = last ? nB : cB + (size_t)(t + 2) * kstep;
;             const char* a3 = a2 + kstep; const char* b3 = b2 + kstep;
;             GP_LDB(B0, 0, 0); GP_LDB(B1, 0, 1); GP_SCHED; GP_LDA(At, 0, 0); GP_STAGE(GP_SA(1, 1), a1 + hstepA, voffA);
;     ...
;         for (int a = 0; a < 2; ++a)
; #pragma unroll
;             for (int b = 0; b < 2; ++b)
; #pragma unroll
;                 for (int m = 0; m < 4; ++m)
; #pragma unroll
;                     for (int n = 0; n < 2; ++n) acc[a][b][m][n] = (f32x4){0.f, 0.f, 0.f, 0.f};
.LBB0_134:
	s_mov_b64 s[28:29], s[88:89]
	s_mov_b64 s[40:41], s[82:83]
	s_mov_b32 s34, s30
	s_and_b64 s[30:31], s[94:95], exec
	s_cselect_b32 s35, s29, s5
	s_cselect_b32 s42, s28, s4
	s_cselect_b32 s43, s41, s93
	s_cselect_b32 s64, s40, s92
	s_add_u32 s4, s4, 0x40080
	s_addc_u32 s5, s5, 0
	s_mov_b32 s12, s81
	s_add_u32 s81, s92, 0x100
	v_mov_b32_e32 v0, 0
	s_mov_b32 s80, s86
	s_addc_u32 s82, s93, 0
	s_mov_b32 s83, -2
	v_mov_b32_e32 v1, v0
	v_mov_b32_e32 v2, v0
	v_mov_b32_e32 v3, v0
	v_mov_b32_e32 v24, v0
	v_mov_b32_e32 v25, v0
	v_mov_b32_e32 v26, v0
	v_mov_b32_e32 v27, v0
	v_mov_b32_e32 v8, v0
	v_mov_b32_e32 v9, v0
	v_mov_b32_e32 v10, v0
	v_mov_b32_e32 v11, v0
	v_mov_b32_e32 v32, v0
	v_mov_b32_e32 v33, v0
	v_mov_b32_e32 v34, v0
	v_mov_b32_e32 v35, v0
	v_mov_b32_e32 v16, v0
	v_mov_b32_e32 v17, v0
	v_mov_b32_e32 v18, v0
	v_mov_b32_e32 v19, v0
	v_mov_b32_e32 v40, v0
	v_mov_b32_e32 v41, v0
	v_mov_b32_e32 v42, v0
	v_mov_b32_e32 v43, v0
	v_mov_b32_e32 v48, v0
	v_mov_b32_e32 v49, v0
	v_mov_b32_e32 v50, v0
	v_mov_b32_e32 v51, v0
	v_mov_b32_e32 v56, v0
	v_mov_b32_e32 v57, v0
	v_mov_b32_e32 v58, v0
	v_mov_b32_e32 v59, v0
	v_mov_b32_e32 v28, v0
	v_mov_b32_e32 v29, v0
	v_mov_b32_e32 v30, v0
	v_mov_b32_e32 v31, v0
	v_mov_b32_e32 v4, v0
	v_mov_b32_e32 v5, v0
	v_mov_b32_e32 v6, v0
	v_mov_b32_e32 v7, v0
	v_mov_b32_e32 v36, v0
	v_mov_b32_e32 v37, v0
	v_mov_b32_e32 v38, v0
	v_mov_b32_e32 v39, v0
	v_mov_b32_e32 v12, v0
	v_mov_b32_e32 v13, v0
	v_mov_b32_e32 v14, v0
	v_mov_b32_e32 v15, v0
	v_mov_b32_e32 v44, v0
	v_mov_b32_e32 v45, v0
	v_mov_b32_e32 v46, v0
	v_mov_b32_e32 v47, v0
	v_mov_b32_e32 v20, v0
	v_mov_b32_e32 v21, v0
	v_mov_b32_e32 v22, v0
	v_mov_b32_e32 v23, v0
	v_mov_b32_e32 v60, v0
	v_mov_b32_e32 v61, v0
	v_mov_b32_e32 v62, v0
	v_mov_b32_e32 v63, v0
	v_mov_b32_e32 v52, v0
	v_mov_b32_e32 v53, v0
	v_mov_b32_e32 v54, v0
	v_mov_b32_e32 v55, v0
	v_mov_b32_e32 v64, v0
	v_mov_b32_e32 v65, v0
	v_mov_b32_e32 v66, v0
	v_mov_b32_e32 v67, v0
	v_mov_b32_e32 v88, v0
	v_mov_b32_e32 v89, v0
	v_mov_b32_e32 v90, v0
	v_mov_b32_e32 v91, v0
	v_mov_b32_e32 v72, v0
	v_mov_b32_e32 v73, v0
	v_mov_b32_e32 v74, v0
	v_mov_b32_e32 v75, v0
	v_mov_b32_e32 v96, v0
	v_mov_b32_e32 v97, v0
	v_mov_b32_e32 v98, v0
	v_mov_b32_e32 v99, v0
	v_mov_b32_e32 v80, v0
	v_mov_b32_e32 v81, v0
	v_mov_b32_e32 v82, v0
	v_mov_b32_e32 v83, v0
	v_mov_b32_e32 v104, v0
	v_mov_b32_e32 v105, v0
	v_mov_b32_e32 v106, v0
	v_mov_b32_e32 v107, v0
	v_mov_b32_e32 v112, v0
	v_mov_b32_e32 v113, v0
	v_mov_b32_e32 v114, v0
	v_mov_b32_e32 v115, v0
	v_mov_b32_e32 v120, v0
	v_mov_b32_e32 v121, v0
	v_mov_b32_e32 v122, v0
	v_mov_b32_e32 v123, v0
	v_mov_b32_e32 v92, v0
	v_mov_b32_e32 v93, v0
	v_mov_b32_e32 v94, v0
	v_mov_b32_e32 v95, v0
	v_mov_b32_e32 v68, v0
	v_mov_b32_e32 v69, v0
	v_mov_b32_e32 v70, v0
	v_mov_b32_e32 v71, v0
	v_mov_b32_e32 v100, v0
	v_mov_b32_e32 v101, v0
	v_mov_b32_e32 v102, v0
	v_mov_b32_e32 v103, v0
	v_mov_b32_e32 v76, v0
	v_mov_b32_e32 v77, v0
	v_mov_b32_e32 v78, v0
	v_mov_b32_e32 v79, v0
	v_mov_b32_e32 v108, v0
	v_mov_b32_e32 v109, v0
	v_mov_b32_e32 v110, v0
	v_mov_b32_e32 v111, v0
	v_mov_b32_e32 v84, v0
	v_mov_b32_e32 v85, v0
	v_mov_b32_e32 v86, v0
	v_mov_b32_e32 v87, v0
	v_mov_b32_e32 v124, v0
	v_mov_b32_e32 v125, v0
	v_mov_b32_e32 v126, v0
	v_mov_b32_e32 v127, v0
	v_mov_b32_e32 v116, v0
	v_mov_b32_e32 v117, v0
	v_mov_b32_e32 v118, v0
	v_mov_b32_e32 v119, v0
	.p2align	6

; template <class Epi, class Sched>
; __device__ __forceinline__ void gemm_phase(LAS unsigned char* lds, const int lda, const int ldb, const int K, const Sched& S, const Epi& E, const int widx) {
;     ...
;         for (int t = 0; t < nt; t += 2) {
;             const bool last = (t == nt - 2);
;             const char* a1 = cA + (size_t)(t + 1) * kstep;
;             const char* a2 = last ? nA : cA + (size_t)(t + 2) * kstep; const char* b2 = last ? nB : cB + (size_t)(t + 2) * kstep;
;             const char* a3 = a2 + kstep; const char* b3 = b2 + kstep;
.LBB0_544:
	s_add_u32 s28, s28, 0x40080
	s_addc_u32 s29, s29, 0
	s_add_u32 s4, s66, 0x100
	s_addc_u32 s39, s67, 0
	s_mov_b32 s41, -2
	.p2align	6

; #define GP_STAGE(bufoff, gbase, voff) do { _Pragma("unroll") for (int _i = 0; _i < 2; ++_i) \
;         __builtin_amdgcn_global_load_lds((const unsigned*)((const char*)(gbase) + (voff)[_i]), (LAS unsigned*)(lds + (bufoff) + ldsw + _i * 8192), 16, 0, 0); } while (0)
; #define GP_LDA(dst, b, h) do { _Pragma("unroll") for (int m = 0; m < 4; ++m) _Pragma("unroll") for (int k = 0; k < 2; ++k) dst[m][k] = *(const LAS bf16x8*)(lds + GP_SA(b, h) + aoff + m * 2048 + k * 1024); } while (0)
; #define GP_LDB(dst, b, h) do { _Pragma("unroll") for (int n = 0; n < 2; ++n) _Pragma("unroll") for (int k = 0; k < 2; ++k) dst[n][k] = *(const LAS bf16x8*)(lds + GP_SB(b, h) + boff + n * 2048 + k * 1024); } while (0)
; #define GP_SCHED __builtin_amdgcn_sched_barrier(0)
; template <class Epi, class Sched>
; __device__ __forceinline__ void gemm_phase(LAS unsigned char* lds, const int lda, const int ldb, const int K, const Sched& S, const Epi& E, const int widx) {
;     ...
;         const bool has_next = S.next(ui + 1, nxt);
;         const char* nA = has_next ? nxt.A : cA; const char* nB = has_next ? nxt.B : cB;
;         for (int t = 0; t < nt; t += 2) {
;             const bool last = (t == nt - 2);
;             const char* a1 = cA + (size_t)(t + 1) * kstep;
;             const char* a2 = last ? nA : cA + (size_t)(t + 2) * kstep; const char* b2 = last ? nB : cB + (size_t)(t + 2) * kstep;
;             const char* a3 = a2 + kstep; const char* b3 = b2 + kstep;
;             GP_LDB(B0, 0, 0); GP_LDB(B1, 0, 1); GP_SCHED; GP_LDA(At, 0, 0); GP_STAGE(GP_SA(1, 1), a1 + hstepA, voffA);
;     ...
;         for (int a = 0; a < 2; ++a)
; #pragma unroll
;             for (int b = 0; b < 2; ++b)
; #pragma unroll
;                 for (int m = 0; m < 4; ++m)
; #pragma unroll
;                     for (int n = 0; n < 2; ++n) acc[a][b][m][n] = (f32x4){0.f, 0.f, 0.f, 0.f};
.LBB0_628:
	s_add_u32 s40, s28, 0x40080
	s_addc_u32 s41, s29, 0
	s_add_u32 s21, s42, 0x100
	v_mov_b32_e32 v0, 0
	s_addc_u32 s42, s43, 0
	s_mov_b32 s43, -2
	s_waitcnt lgkmcnt(0)
	v_mov_b32_e32 v1, v0
	v_mov_b32_e32 v2, v0
	v_mov_b32_e32 v3, v0
	v_mov_b32_e32 v4, v0
	v_mov_b32_e32 v5, v0
	v_mov_b32_e32 v6, v0
	v_mov_b32_e32 v7, v0
	v_mov_b32_e32 v16, v0
	v_mov_b32_e32 v17, v0
	v_mov_b32_e32 v18, v0
	v_mov_b32_e32 v19, v0
	v_mov_b32_e32 v20, v0
	v_mov_b32_e32 v21, v0
	v_mov_b32_e32 v22, v0
	v_mov_b32_e32 v23, v0
	v_mov_b32_e32 v32, v0
	v_mov_b32_e32 v33, v0
	v_mov_b32_e32 v34, v0
	v_mov_b32_e32 v35, v0
	v_mov_b32_e32 v36, v0
	v_mov_b32_e32 v37, v0
	v_mov_b32_e32 v38, v0
	v_mov_b32_e32 v39, v0
	v_mov_b32_e32 v48, v0
	v_mov_b32_e32 v49, v0
	v_mov_b32_e32 v50, v0
	v_mov_b32_e32 v51, v0
	v_mov_b32_e32 v52, v0
	v_mov_b32_e32 v53, v0
	v_mov_b32_e32 v54, v0
	v_mov_b32_e32 v55, v0
	v_mov_b32_e32 v8, v0
	v_mov_b32_e32 v9, v0
	v_mov_b32_e32 v10, v0
	v_mov_b32_e32 v11, v0
	v_mov_b32_e32 v12, v0
	v_mov_b32_e32 v13, v0
	v_mov_b32_e32 v14, v0
	v_mov_b32_e32 v15, v0
	v_mov_b32_e32 v24, v0
	v_mov_b32_e32 v25, v0
	v_mov_b32_e32 v26, v0
	v_mov_b32_e32 v27, v0
	v_mov_b32_e32 v28, v0
	v_mov_b32_e32 v29, v0
	v_mov_b32_e32 v30, v0
	v_mov_b32_e32 v31, v0
	v_mov_b32_e32 v40, v0
	v_mov_b32_e32 v41, v0
	v_mov_b32_e32 v42, v0
	v_mov_b32_e32 v43, v0
	v_mov_b32_e32 v44, v0
	v_mov_b32_e32 v45, v0
	v_mov_b32_e32 v46, v0
	v_mov_b32_e32 v47, v0
	v_mov_b32_e32 v56, v0
	v_mov_b32_e32 v57, v0
	v_mov_b32_e32 v58, v0
	v_mov_b32_e32 v59, v0
	v_mov_b32_e32 v60, v0
	v_mov_b32_e32 v61, v0
	v_mov_b32_e32 v62, v0
	v_mov_b32_e32 v63, v0
	v_mov_b32_e32 v64, v0
	v_mov_b32_e32 v65, v0
	v_mov_b32_e32 v66, v0
	v_mov_b32_e32 v67, v0
	v_mov_b32_e32 v68, v0
	v_mov_b32_e32 v69, v0
	v_mov_b32_e32 v70, v0
	v_mov_b32_e32 v71, v0
	v_mov_b32_e32 v80, v0
	v_mov_b32_e32 v81, v0
	v_mov_b32_e32 v82, v0
	v_mov_b32_e32 v83, v0
	v_mov_b32_e32 v84, v0
	v_mov_b32_e32 v85, v0
	v_mov_b32_e32 v86, v0
	v_mov_b32_e32 v87, v0
	v_mov_b32_e32 v96, v0
	v_mov_b32_e32 v97, v0
	v_mov_b32_e32 v98, v0
	v_mov_b32_e32 v99, v0
	v_mov_b32_e32 v100, v0
	v_mov_b32_e32 v101, v0
	v_mov_b32_e32 v102, v0
	v_mov_b32_e32 v103, v0
	v_mov_b32_e32 v112, v0
	v_mov_b32_e32 v113, v0
	v_mov_b32_e32 v114, v0
	v_mov_b32_e32 v115, v0
	v_mov_b32_e32 v116, v0
	v_mov_b32_e32 v117, v0
	v_mov_b32_e32 v118, v0
	v_mov_b32_e32 v119, v0
	v_mov_b32_e32 v72, v0
	v_mov_b32_e32 v73, v0
	v_mov_b32_e32 v74, v0
	v_mov_b32_e32 v75, v0
	v_mov_b32_e32 v76, v0
	v_mov_b32_e32 v77, v0
	v_mov_b32_e32 v78, v0
	v_mov_b32_e32 v79, v0
	v_mov_b32_e32 v88, v0
	v_mov_b32_e32 v89, v0
	v_mov_b32_e32 v90, v0
	v_mov_b32_e32 v91, v0
	v_mov_b32_e32 v92, v0
	v_mov_b32_e32 v93, v0
	v_mov_b32_e32 v94, v0
	v_mov_b32_e32 v95, v0
	v_mov_b32_e32 v104, v0
	v_mov_b32_e32 v105, v0
	v_mov_b32_e32 v106, v0
	v_mov_b32_e32 v107, v0
	v_mov_b32_e32 v108, v0
	v_mov_b32_e32 v109, v0
	v_mov_b32_e32 v110, v0
	v_mov_b32_e32 v111, v0
	v_mov_b32_e32 v120, v0
	v_mov_b32_e32 v121, v0
	v_mov_b32_e32 v122, v0
	v_mov_b32_e32 v123, v0
	v_mov_b32_e32 v124, v0
	v_mov_b32_e32 v125, v0
	v_mov_b32_e32 v126, v0
	v_mov_b32_e32 v127, v0
	.p2align	6
